# panel-ready wait before the first GEMM tile: the acquire invalidate is issued before the poll loop (as the grid barrier does) so it overlaps the wait
# speedup vs baseline: 1.0161x; 1.0028x over previous
.LBB0_196:
	s_andn2_b64 vcc, exec, s[4:5]
	s_cbranch_vccnz .LBB0_276
	s_add_u32 s12, s20, 0x453c200
	s_addc_u32 s13, s21, 0
	v_cmp_gt_i32_e64 s[4:5], 64, v148
	s_and_saveexec_b64 s[6:7], s[4:5]
	s_cbranch_execz .LBB0_214
	s_lshl_b32 s16, s14, 6
	s_memrealtime s[8:9]
	buffer_inv sc1
	s_ashr_i32 s17, s16, 31
	s_lshl_b64 s[16:17], s[16:17], 2
	s_add_u32 s16, s24, s16
	s_addc_u32 s17, s25, s17
	s_mov_b32 s11, 1
	v_mov_b64_e32 v[0:1], s[16:17]
	v_mov_b64_e32 v[2:3], 0x1e8481
	s_branch .LBB0_201

.LBB0_1433:
	s_andn2_b64 vcc, exec, s[4:5]
	s_cbranch_vccnz .LBB0_1513
	s_add_u32 s14, s16, 0x453c200
	s_addc_u32 s15, s17, 0
	v_cmp_gt_i32_e64 s[4:5], 64, v150
	s_and_saveexec_b64 s[6:7], s[4:5]
	s_cbranch_execz .LBB0_1451
	s_lshl_b32 s22, s20, 6
	s_memrealtime s[8:9]
	buffer_inv sc1
	s_ashr_i32 s23, s22, 31
	s_lshl_b64 s[22:23], s[22:23], 2
	s_add_u32 s22, s18, s22
	s_addc_u32 s23, s19, s23
	s_mov_b32 s11, 1
	v_mov_b64_e32 v[0:1], s[22:23]
	v_mov_b64_e32 v[2:3], 0x1e8481
	s_branch .LBB0_1438

.LBB0_1704:
	s_andn2_b64 vcc, exec, s[4:5]
	s_cbranch_vccnz .LBB0_1784
	s_add_u32 s12, s10, 0x453c200
	s_addc_u32 s13, s11, 0
	v_cmp_gt_i32_e64 s[4:5], 64, v59
	s_and_saveexec_b64 s[6:7], s[4:5]
	s_cbranch_execz .LBB0_1722
	s_lshl_b32 s14, s44, 6
	s_memrealtime s[8:9]
	buffer_inv sc1
	s_ashr_i32 s15, s14, 31
	s_lshl_b64 s[14:15], s[14:15], 2
	s_add_u32 s14, s16, s14
	s_addc_u32 s15, s17, s15
	s_mov_b32 s20, 1
	v_mov_b64_e32 v[0:1], s[14:15]
	v_mov_b64_e32 v[2:3], 0x1e8481
	s_branch .LBB0_1709

.LBB0_2094:
	s_andn2_b64 vcc, exec, s[4:5]
	s_cbranch_vccnz .LBB0_2168
	s_add_u32 s12, s10, 0x453c200
	s_addc_u32 s13, s11, 0
	v_cmp_gt_i32_e64 s[4:5], 64, v59
	s_and_saveexec_b64 s[6:7], s[4:5]
	s_cbranch_execz .LBB0_2112
	s_mul_i32 s15, s54, 0xc0
	s_add_i32 s20, s15, 0xbf
	s_ashr_i32 s15, s15, 2
	s_and_b32 s18, s15, 0xffffffc0
	s_ashr_i32 s15, s20, 2
	s_ashr_i32 s19, s18, 31
	s_and_b32 s20, s15, 0xffffffc0
	s_memrealtime s[8:9]
	buffer_inv sc1
	s_ashr_i32 s21, s20, 31
	s_lshl_b64 s[18:19], s[18:19], 2
	s_add_u32 s22, s16, s18
	s_addc_u32 s23, s17, s19
	s_lshl_b64 s[18:19], s[20:21], 2
	s_add_u32 s18, s16, s18
	s_addc_u32 s19, s17, s19
	s_mov_b32 s15, 1
	v_mov_b64_e32 v[0:1], s[22:23]
	v_mov_b64_e32 v[2:3], 0x1e8481
	s_branch .LBB0_2099

.LBB0_3190:
	s_andn2_b64 vcc, exec, s[4:5]
	s_cbranch_vccnz .LBB0_3264
	s_add_u32 s12, s18, 0x453c200
	s_addc_u32 s13, s19, 0
	v_cmp_gt_i32_e64 s[4:5], 64, v74
	s_and_saveexec_b64 s[6:7], s[4:5]
	s_cbranch_execz .LBB0_3208
	s_mul_i32 s10, s60, 0xc0
	s_add_i32 s15, s10, 0xbf
	s_ashr_i32 s10, s10, 2
	s_andn2_b32 s10, s10, 63
	s_ashr_i32 s15, s15, 2
	s_ashr_i32 s11, s10, 31
	s_and_b32 s20, s15, 0xffffffc0
	s_memrealtime s[8:9]
	buffer_inv sc1
	s_ashr_i32 s21, s20, 31
	s_lshl_b64 s[10:11], s[10:11], 2
	s_add_u32 s22, s16, s10
	s_addc_u32 s23, s17, s11
	s_lshl_b64 s[10:11], s[20:21], 2
	s_add_u32 s10, s16, s10
	s_addc_u32 s11, s17, s11
	s_mov_b32 s15, 1
	v_mov_b64_e32 v[0:1], s[22:23]
	v_mov_b64_e32 v[2:3], 0x1e8481
	s_branch .LBB0_3195
